# also refresh U|VA in the P1->P2 barrier and touch SSE before P5
# baseline (speedup 1.0000x reference)
.Lmy_touchw2_skip:
	v_readfirstlane_b32 s1, v0
	s_cmp_lt_u32 s1, 64
	s_cbranch_scc1 .Lmy_touchuva_skip
	v_readlane_b32 s98, v251, 20
	v_readlane_b32 s99, v251, 21
	s_lshl_b32 s0, s70, 17
	s_add_u32 s0, s0, 0x6800000
	s_add_u32 s98, s98, s0
	s_addc_u32 s99, s99, 0
	v_add_u32_e32 v252, 0xffffffc0, v0
	v_lshlrev_b32_e32 v252, 6, v252
	s_nop 1
	global_load_dword v255, v252, s[98:99]
	v_add_u32_e32 v253, 0x7000, v252
	v_and_b32_e32 v253, 0x1ffc0, v253
	global_load_dword v255, v253, s[98:99]
	v_add_u32_e32 v253, 0xe000, v252
	v_and_b32_e32 v253, 0x1ffc0, v253
	global_load_dword v255, v253, s[98:99]
	v_add_u32_e32 v253, 0x15000, v252
	v_and_b32_e32 v253, 0x1ffc0, v253
	global_load_dword v255, v253, s[98:99]
	v_add_u32_e32 v253, 0x1c000, v252
	v_and_b32_e32 v253, 0x1ffc0, v253
	global_load_dword v255, v253, s[98:99]

.Lmy_t5_skip:
	v_readfirstlane_b32 s98, v0
	s_cmp_lt_u32 s98, 64
	s_cbranch_scc1 .Lmy_t5b_skip
	v_readlane_b32 s98, v251, 20
	v_readlane_b32 s99, v251, 21
	s_lshr_b32 s100, s70, 3
	s_and_b32 s100, s100, 7
	s_and_b32 s101, s70, 7
	s_lshl_b32 s101, s101, 3
	s_or_b32 s100, s100, s101
	s_lshl_b32 s100, s100, 14
	s_add_u32 s100, s100, 0x2400000
	s_add_u32 s98, s98, s100
	s_addc_u32 s99, s99, 0
	v_and_b32_e32 v252, 0xff, v0
	v_lshlrev_b32_e32 v252, 6, v252
	s_nop 1
	global_load_dword v255, v252, s[98:99]
